# epilogue cache-warming prefetch of later row batches in EpiRes (WOUT, FFN-b) and BR gate epilogue
# baseline (speedup 1.0000x reference)
;     __device__ __forceinline__ void operator()(const f32x4 (&acc)[2][2][4][2], const Unit& u, int wr, int wc, int fr, int fq) const {
;         typedef unsigned u32x2 __attribute__((ext_vector_type(2)));
;         const int b = (u.pm * BM + row_off) >> 11;
;         const int col0 = u.pn * BM + wc * 32 + 4 * fq;
;         f32x4 gv[2][2];
; #pragma unroll
;         for (int bj = 0; bj < 2; ++bj)
; #pragma unroll
;             for (int n = 0; n < 2; ++n) gv[bj][n] = *(const PG8_GAS f32x4*)(gate + (size_t)b * 9216 + col0 + bj * HALF + n * 16) * coef;
; #pragma unroll
;         for (int ai = 0; ai < 2; ++ai)
; #pragma unroll
;             for (int mh = 0; mh < 2; ++mh) {
;                 u32x4 raw[2][2][2];
; #pragma unroll
;                 for (int mm = 0; mm < 2; ++mm) {
;                     const size_t off = (size_t)(u.pm * BM + ai * HALF + wr * 64 + (2 * mh + mm) * 16 + fr) * 1024 + col0;
; #pragma unroll
;                     for (int bj = 0; bj < 2; ++bj)
; #pragma unroll
;                         for (int n = 0; n < 2; ++n) {
;                             const size_t o = off + bj * HALF + n * 16;
;                             if (in_bf) { const u32x2 w = *(const PG8_GAS u32x2*)((const bf16_t*)base + o); raw[mm][bj][n].x = w.x; raw[mm][bj][n].y = w.y; }
;                             else raw[mm][bj][n] = *(const PG8_GAS u32x4*)((const float*)base + o);
;                         }
;                 }
;                 asm volatile("" ::: "memory");
; #pragma unroll
;                 for (int mm = 0; mm < 2; ++mm) {
;                     const int m = 2 * mh + mm;
;                     const size_t off = (size_t)(u.pm * BM + ai * HALF + wr * 64 + m * 16 + fr) * 1024 + col0;
; #pragma unroll
;                     for (int bj = 0; bj < 2; ++bj)
; #pragma unroll
;                         for (int n = 0; n < 2; ++n) {
;                             const size_t o = off + bj * HALF + n * 16;
;                             const u32x4 w4 = raw[mm][bj][n];
;                             f32x4 bs;
;                             if (in_bf) bs = (f32x4){bf_lo(w4.x), bf_hi(w4.x), bf_lo(w4.y), bf_hi(w4.y)};
;                             else bs = (f32x4){__uint_as_float(w4.x), __uint_as_float(w4.y), __uint_as_float(w4.z), __uint_as_float(w4.w)};
;                             const f32x4 r = bs + gv[bj][n] * acc[ai][bj][m][n];
.LBB0_73:
	v_lshl_add_u32 v150, s48, 8, v154
	v_lshl_or_b32 v128, s59, 8, v156
	v_ashrrev_i32_e32 v151, 31, v150
	v_ashrrev_i32_e32 v129, 31, v128
	v_lshlrev_b64 v[130:131], 11, v[150:151]
	v_lshl_add_u64 v[130:131], s[8:9], 0, v[130:131]
	v_lshlrev_b64 v[152:153], 1, v[128:129]
	s_ashr_i32 s2, s48, 3
	v_lshl_add_u64 v[158:159], v[130:131], 0, v[152:153]
	s_mul_hi_i32 s13, s2, 0x9000
	s_mul_i32 s2, s2, 0x9000
	v_or_b32_e32 v130, 16, v150
	s_add_u32 s24, s29, s2
	v_ashrrev_i32_e32 v131, 31, v130
	s_addc_u32 s25, s38, s13
	v_lshlrev_b64 v[130:131], 11, v[130:131]
	global_load_dwordx2 v[160:161], v[158:159], off
	global_load_dwordx2 v[162:163], v[158:159], off offset:32
	global_load_dwordx2 v[164:165], v[158:159], off offset:256
	global_load_dwordx2 v[166:167], v[158:159], off offset:288
	v_lshl_add_u64 v[128:129], v[128:129], 2, s[24:25]
	v_lshl_add_u64 v[168:169], s[8:9], 0, v[130:131]
	global_load_dwordx4 v[140:143], v[128:129], off
	global_load_dwordx4 v[136:139], v[128:129], off offset:64
	global_load_dwordx4 v[132:135], v[128:129], off offset:512
	v_lshl_add_u64 v[168:169], v[168:169], 0, v[152:153]
	global_load_dwordx4 v[128:131], v[128:129], off offset:576
	s_nop 0
	global_load_dwordx2 v[170:171], v[168:169], off
	global_load_dwordx2 v[172:173], v[168:169], off offset:32
	global_load_dwordx2 v[174:175], v[168:169], off offset:256
	global_load_dwordx2 v[176:177], v[168:169], off offset:288
	s_mov_b64 s[98:99], 0x10000
	v_lshl_add_u64 v[250:251], v[158:159], 0, s[98:99]
	global_load_dword v252, v[250:251], off
	global_load_dword v252, v[250:251], off offset:256
	s_mov_b64 s[98:99], 0x8000
	v_lshl_add_u64 v[250:251], v[250:251], 0, s[98:99]
	global_load_dword v252, v[250:251], off
	global_load_dword v252, v[250:251], off offset:256
	s_mov_b64 s[98:99], 0x28000
	v_lshl_add_u64 v[250:251], v[250:251], 0, s[98:99]
	global_load_dword v252, v[250:251], off
	global_load_dword v252, v[250:251], off offset:256
	s_mov_b64 s[98:99], 0x8000
	v_lshl_add_u64 v[250:251], v[250:251], 0, s[98:99]
	global_load_dword v252, v[250:251], off
	global_load_dword v252, v[250:251], off offset:256
	s_mov_b64 s[98:99], 0x8000
	v_lshl_add_u64 v[250:251], v[250:251], 0, s[98:99]
	global_load_dword v252, v[250:251], off
	global_load_dword v252, v[250:251], off offset:256
	s_mov_b64 s[98:99], 0x8000
	v_lshl_add_u64 v[250:251], v[250:251], 0, s[98:99]
	global_load_dword v252, v[250:251], off
	global_load_dword v252, v[250:251], off offset:256
	s_andn2_b64 vcc, exec, s[42:43]
	s_mov_b64 s[42:43], -1
	s_waitcnt vmcnt(0)
	v_lshlrev_b32_e32 v178, 16, v160
	v_and_b32_e32 v179, 0xffff0000, v160
	v_lshlrev_b32_e32 v160, 16, v161
	v_and_b32_e32 v161, 0xffff0000, v161
	v_lshlrev_b32_e32 v180, 16, v162
	v_and_b32_e32 v181, 0xffff0000, v162
	v_lshlrev_b32_e32 v162, 16, v163
	v_and_b32_e32 v163, 0xffff0000, v163
	v_lshlrev_b32_e32 v182, 16, v164
	v_and_b32_e32 v183, 0xffff0000, v164
	v_lshlrev_b32_e32 v164, 16, v165
	v_and_b32_e32 v165, 0xffff0000, v165
	v_lshlrev_b32_e32 v184, 16, v166
	v_and_b32_e32 v185, 0xffff0000, v166
	v_lshlrev_b32_e32 v166, 16, v167
	v_and_b32_e32 v167, 0xffff0000, v167
	v_pk_fma_f32 v[126:127], v[126:127], v[142:143], v[160:161]
	v_pk_fma_f32 v[122:123], v[122:123], v[138:139], v[162:163]
	v_pk_fma_f32 v[118:119], v[118:119], v[134:135], v[164:165]
	v_pk_fma_f32 v[114:115], v[114:115], v[130:131], v[166:167]
	v_lshlrev_b32_e32 v160, 16, v170
	v_and_b32_e32 v161, 0xffff0000, v170
	v_lshlrev_b32_e32 v162, 16, v171
	v_and_b32_e32 v163, 0xffff0000, v171
	v_lshlrev_b32_e32 v164, 16, v172
	v_and_b32_e32 v165, 0xffff0000, v172
	v_lshlrev_b32_e32 v166, 16, v173
	v_and_b32_e32 v167, 0xffff0000, v173
	v_lshlrev_b32_e32 v170, 16, v174
	v_and_b32_e32 v171, 0xffff0000, v174
	v_lshlrev_b32_e32 v172, 16, v175
	v_and_b32_e32 v173, 0xffff0000, v175
	v_pk_fma_f32 v[124:125], v[124:125], v[140:141], v[178:179]
	v_pk_fma_f32 v[110:111], v[110:111], v[142:143], v[162:163]
	v_pk_fma_f32 v[108:109], v[108:109], v[140:141], v[160:161]
	v_pk_fma_f32 v[102:103], v[102:103], v[134:135], v[172:173]
	v_pk_fma_f32 v[100:101], v[100:101], v[132:133], v[170:171]
	v_pk_fma_f32 v[120:121], v[120:121], v[136:137], v[180:181]
	v_pk_fma_f32 v[116:117], v[116:117], v[132:133], v[182:183]
	v_pk_fma_f32 v[112:113], v[112:113], v[128:129], v[184:185]
	v_cvt_pk_bf16_f32 v124, v124, v125
	v_cvt_pk_bf16_f32 v125, v126, v127
	v_pk_fma_f32 v[106:107], v[106:107], v[138:139], v[166:167]
	v_pk_fma_f32 v[104:105], v[104:105], v[136:137], v[164:165]
	v_cvt_pk_bf16_f32 v108, v108, v109
	v_cvt_pk_bf16_f32 v109, v110, v111
	v_cvt_pk_bf16_f32 v100, v100, v101
	v_cvt_pk_bf16_f32 v101, v102, v103
	v_cvt_pk_bf16_f32 v120, v120, v121
	v_cvt_pk_bf16_f32 v121, v122, v123
	v_cvt_pk_bf16_f32 v116, v116, v117
	v_cvt_pk_bf16_f32 v117, v118, v119
	v_cvt_pk_bf16_f32 v112, v112, v113
	v_cvt_pk_bf16_f32 v113, v114, v115
	global_store_dwordx2 v[158:159], v[124:125], off
	global_store_dwordx2 v[158:159], v[120:121], off offset:32
	global_store_dwordx2 v[158:159], v[116:117], off offset:256
	global_store_dwordx2 v[158:159], v[112:113], off offset:288
	v_cvt_pk_bf16_f32 v104, v104, v105
	v_cvt_pk_bf16_f32 v105, v106, v107
	global_store_dwordx2 v[168:169], v[108:109], off
	global_store_dwordx2 v[168:169], v[104:105], off offset:32
	global_store_dwordx2 v[168:169], v[100:101], off offset:256
	v_lshlrev_b32_e32 v100, 16, v176
	v_and_b32_e32 v101, 0xffff0000, v176
	v_lshlrev_b32_e32 v102, 16, v177
	v_and_b32_e32 v103, 0xffff0000, v177
	v_pk_fma_f32 v[98:99], v[98:99], v[130:131], v[102:103]
	v_pk_fma_f32 v[96:97], v[96:97], v[128:129], v[100:101]
	v_or_b32_e32 v106, 48, v150
	v_cvt_pk_bf16_f32 v96, v96, v97
	v_cvt_pk_bf16_f32 v97, v98, v99
	global_store_dwordx2 v[168:169], v[96:97], off offset:288
	v_or_b32_e32 v96, 32, v150
	v_ashrrev_i32_e32 v97, 31, v96
	v_lshlrev_b64 v[96:97], 11, v[96:97]
	v_lshl_add_u64 v[96:97], s[8:9], 0, v[96:97]
	v_lshl_add_u64 v[96:97], v[96:97], 0, v[152:153]
	v_ashrrev_i32_e32 v107, 31, v106
	global_load_dwordx2 v[98:99], v[96:97], off
	global_load_dwordx2 v[100:101], v[96:97], off offset:32
	global_load_dwordx2 v[102:103], v[96:97], off offset:256
	global_load_dwordx2 v[104:105], v[96:97], off offset:288
	v_lshlrev_b64 v[106:107], 11, v[106:107]
	v_lshl_add_u64 v[106:107], s[8:9], 0, v[106:107]
	v_lshl_add_u64 v[106:107], v[106:107], 0, v[152:153]
	global_load_dwordx2 v[108:109], v[106:107], off
	global_load_dwordx2 v[110:111], v[106:107], off offset:32
	global_load_dwordx2 v[112:113], v[106:107], off offset:256
	global_load_dwordx2 v[114:115], v[106:107], off offset:288
	s_waitcnt vmcnt(7)
; #define PG8_GAS __attribute__((address_space(1)))
; __device__ __forceinline__ unsigned cvt_pk_bf16(float lo, float hi) { const f32x2_ v = {lo, hi}; const bf16x2_ b = __builtin_convertvector(v, bf16x2_); return __builtin_bit_cast(unsigned, b); }
;     __device__ __forceinline__ void operator()(const f32x4 (&acc)[2][2][4][2], const Unit& u, int wr, int wc, int fr, int fq) const {
;     ...
;                 u32x4 raw[2][2][2];
; #pragma unroll
;                 for (int mm = 0; mm < 2; ++mm) {
;                     const size_t off = (size_t)(u.pm * BM + ai * HALF + wr * 64 + (2 * mh + mm) * 16 + fr) * 1024 + col0;
; #pragma unroll
;                     for (int bj = 0; bj < 2; ++bj)
; #pragma unroll
;                         for (int n = 0; n < 2; ++n) {
;                             const size_t o = off + bj * HALF + n * 16;
;                             if (in_bf) { const u32x2 w = *(const PG8_GAS u32x2*)((const bf16_t*)base + o); raw[mm][bj][n].x = w.x; raw[mm][bj][n].y = w.y; }
;                             else raw[mm][bj][n] = *(const PG8_GAS u32x4*)((const float*)base + o);
;                         }
;                 }
;                 asm volatile("" ::: "memory");
; #pragma unroll
;                 for (int mm = 0; mm < 2; ++mm) {
;                     const int m = 2 * mh + mm;
;                     const size_t off = (size_t)(u.pm * BM + ai * HALF + wr * 64 + m * 16 + fr) * 1024 + col0;
; #pragma unroll
;                     for (int bj = 0; bj < 2; ++bj)
; #pragma unroll
;                         for (int n = 0; n < 2; ++n) {
;                             const size_t o = off + bj * HALF + n * 16;
;                             const u32x4 w4 = raw[mm][bj][n];
;                             f32x4 bs;
;                             if (in_bf) bs = (f32x4){bf_lo(w4.x), bf_hi(w4.x), bf_lo(w4.y), bf_hi(w4.y)};
;                             else bs = (f32x4){__uint_as_float(w4.x), __uint_as_float(w4.y), __uint_as_float(w4.z), __uint_as_float(w4.w)};
;                             const f32x4 r = bs + gv[bj][n] * acc[ai][bj][m][n];
;                             if (out_bf) { u32x2 w; w.x = cvt_pk_bf16(r[0], r[1]); w.y = cvt_pk_bf16(r[2], r[3]); *(PG8_GAS u32x2*)((bf16_t*)out + o) = w; }
;                             else *(PG8_GAS f32x4*)((float*)out + o) = r;
;                         }
;                 }
;                 asm volatile("" ::: "memory");
	v_lshlrev_b32_e32 v116, 16, v98
	v_and_b32_e32 v117, 0xffff0000, v98
	v_lshlrev_b32_e32 v98, 16, v99
	v_and_b32_e32 v99, 0xffff0000, v99
	s_waitcnt vmcnt(4)
	v_lshlrev_b32_e32 v122, 16, v104
	v_and_b32_e32 v123, 0xffff0000, v104
	v_lshlrev_b32_e32 v104, 16, v105
	v_and_b32_e32 v105, 0xffff0000, v105
	v_lshlrev_b32_e32 v118, 16, v100
	v_and_b32_e32 v119, 0xffff0000, v100
	v_lshlrev_b32_e32 v100, 16, v101
	v_and_b32_e32 v101, 0xffff0000, v101
	v_lshlrev_b32_e32 v120, 16, v102
	v_and_b32_e32 v121, 0xffff0000, v102
	v_lshlrev_b32_e32 v102, 16, v103
	v_and_b32_e32 v103, 0xffff0000, v103
	s_waitcnt vmcnt(3)
	v_lshlrev_b32_e32 v124, 16, v108
	v_and_b32_e32 v125, 0xffff0000, v108
	v_lshlrev_b32_e32 v108, 16, v109
	v_and_b32_e32 v109, 0xffff0000, v109
	s_waitcnt vmcnt(2)
	v_lshlrev_b32_e32 v126, 16, v110
	v_and_b32_e32 v127, 0xffff0000, v110
	v_lshlrev_b32_e32 v110, 16, v111
	v_and_b32_e32 v111, 0xffff0000, v111
	v_pk_fma_f32 v[94:95], v[94:95], v[142:143], v[98:99]
	v_pk_fma_f32 v[92:93], v[92:93], v[140:141], v[116:117]
	v_pk_fma_f32 v[74:75], v[74:75], v[130:131], v[104:105]
	v_pk_fma_f32 v[72:73], v[72:73], v[128:129], v[122:123]
	v_pk_fma_f32 v[90:91], v[90:91], v[138:139], v[100:101]
	v_pk_fma_f32 v[88:89], v[88:89], v[136:137], v[118:119]
	v_pk_fma_f32 v[78:79], v[78:79], v[134:135], v[102:103]
	v_pk_fma_f32 v[76:77], v[76:77], v[132:133], v[120:121]
	v_pk_fma_f32 v[86:87], v[86:87], v[142:143], v[108:109]
	v_pk_fma_f32 v[84:85], v[84:85], v[140:141], v[124:125]
	v_pk_fma_f32 v[82:83], v[82:83], v[138:139], v[110:111]
	v_pk_fma_f32 v[80:81], v[80:81], v[136:137], v[126:127]
	v_cvt_pk_bf16_f32 v92, v92, v93
	v_cvt_pk_bf16_f32 v93, v94, v95
	v_cvt_pk_bf16_f32 v72, v72, v73
	v_cvt_pk_bf16_f32 v73, v74, v75
	v_cvt_pk_bf16_f32 v88, v88, v89
	v_cvt_pk_bf16_f32 v89, v90, v91
	v_cvt_pk_bf16_f32 v76, v76, v77
	v_cvt_pk_bf16_f32 v77, v78, v79
	v_cvt_pk_bf16_f32 v74, v84, v85
	v_cvt_pk_bf16_f32 v75, v86, v87
	global_store_dwordx2 v[96:97], v[92:93], off
	global_store_dwordx2 v[96:97], v[88:89], off offset:32
	global_store_dwordx2 v[96:97], v[76:77], off offset:256
	global_store_dwordx2 v[96:97], v[72:73], off offset:288
	global_store_dwordx2 v[106:107], v[74:75], off
	v_cvt_pk_bf16_f32 v72, v80, v81
	v_cvt_pk_bf16_f32 v73, v82, v83
	global_store_dwordx2 v[106:107], v[72:73], off offset:32
	s_waitcnt vmcnt(7)
	v_lshlrev_b32_e32 v72, 16, v112
	v_and_b32_e32 v73, 0xffff0000, v112
	v_lshlrev_b32_e32 v74, 16, v113
	v_and_b32_e32 v75, 0xffff0000, v113
	v_pk_fma_f32 v[70:71], v[70:71], v[134:135], v[74:75]
	v_pk_fma_f32 v[68:69], v[68:69], v[132:133], v[72:73]
	v_add_u32_e32 v74, 0x90, v150
	v_cvt_pk_bf16_f32 v68, v68, v69
	v_cvt_pk_bf16_f32 v69, v70, v71
	global_store_dwordx2 v[106:107], v[68:69], off offset:256
	s_waitcnt vmcnt(7)
	v_lshlrev_b32_e32 v68, 16, v114
	v_and_b32_e32 v69, 0xffff0000, v114
	v_lshlrev_b32_e32 v70, 16, v115
	v_and_b32_e32 v71, 0xffff0000, v115
	v_pk_fma_f32 v[66:67], v[66:67], v[130:131], v[70:71]
	v_pk_fma_f32 v[64:65], v[64:65], v[128:129], v[68:69]
	v_ashrrev_i32_e32 v75, 31, v74
	v_cvt_pk_bf16_f32 v64, v64, v65
	v_cvt_pk_bf16_f32 v65, v66, v67
	global_store_dwordx2 v[106:107], v[64:65], off offset:288
	v_add_u32_e32 v64, 0x80, v150
	v_ashrrev_i32_e32 v65, 31, v64
	v_lshlrev_b64 v[64:65], 11, v[64:65]
	v_lshl_add_u64 v[64:65], s[8:9], 0, v[64:65]
	v_lshl_add_u64 v[64:65], v[64:65], 0, v[152:153]
	global_load_dwordx2 v[66:67], v[64:65], off
	global_load_dwordx2 v[68:69], v[64:65], off offset:32
	global_load_dwordx2 v[70:71], v[64:65], off offset:256
	global_load_dwordx2 v[72:73], v[64:65], off offset:288
	v_lshlrev_b64 v[74:75], 11, v[74:75]
	v_lshl_add_u64 v[74:75], s[8:9], 0, v[74:75]
	v_lshl_add_u64 v[74:75], v[74:75], 0, v[152:153]
	global_load_dwordx2 v[76:77], v[74:75], off
	global_load_dwordx2 v[78:79], v[74:75], off offset:32
	global_load_dwordx2 v[80:81], v[74:75], off offset:256
	global_load_dwordx2 v[82:83], v[74:75], off offset:288
	s_waitcnt vmcnt(7)
	v_lshlrev_b32_e32 v84, 16, v66
	v_and_b32_e32 v85, 0xffff0000, v66
	v_lshlrev_b32_e32 v66, 16, v67
	v_and_b32_e32 v67, 0xffff0000, v67
	s_waitcnt vmcnt(4)
	v_lshlrev_b32_e32 v90, 16, v72
	v_and_b32_e32 v91, 0xffff0000, v72
	v_lshlrev_b32_e32 v72, 16, v73
	v_and_b32_e32 v73, 0xffff0000, v73
	s_waitcnt vmcnt(3)
	v_lshlrev_b32_e32 v92, 16, v76
	v_and_b32_e32 v93, 0xffff0000, v76
	v_lshlrev_b32_e32 v76, 16, v77
	v_and_b32_e32 v77, 0xffff0000, v77
	v_lshlrev_b32_e32 v86, 16, v68
	v_and_b32_e32 v87, 0xffff0000, v68
	v_lshlrev_b32_e32 v68, 16, v69
	v_and_b32_e32 v69, 0xffff0000, v69
	v_lshlrev_b32_e32 v88, 16, v70
	v_and_b32_e32 v89, 0xffff0000, v70
	v_lshlrev_b32_e32 v70, 16, v71
	v_and_b32_e32 v71, 0xffff0000, v71
	v_pk_fma_f32 v[62:63], v[62:63], v[142:143], v[66:67]
	v_pk_fma_f32 v[60:61], v[60:61], v[140:141], v[84:85]
	v_pk_fma_f32 v[46:47], v[46:47], v[130:131], v[72:73]
	v_pk_fma_f32 v[44:45], v[44:45], v[128:129], v[90:91]
	v_pk_fma_f32 v[54:55], v[54:55], v[142:143], v[76:77]
	v_pk_fma_f32 v[52:53], v[52:53], v[140:141], v[92:93]
	v_pk_fma_f32 v[58:59], v[58:59], v[138:139], v[68:69]
	v_pk_fma_f32 v[56:57], v[56:57], v[136:137], v[86:87]
	v_pk_fma_f32 v[50:51], v[50:51], v[134:135], v[70:71]
	v_pk_fma_f32 v[48:49], v[48:49], v[132:133], v[88:89]
	v_cvt_pk_bf16_f32 v60, v60, v61
	v_cvt_pk_bf16_f32 v61, v62, v63
	v_cvt_pk_bf16_f32 v44, v44, v45
	v_cvt_pk_bf16_f32 v45, v46, v47
	v_cvt_pk_bf16_f32 v46, v52, v53
	v_cvt_pk_bf16_f32 v47, v54, v55
	v_cvt_pk_bf16_f32 v56, v56, v57
	v_cvt_pk_bf16_f32 v57, v58, v59
	v_cvt_pk_bf16_f32 v48, v48, v49
	v_cvt_pk_bf16_f32 v49, v50, v51
	global_store_dwordx2 v[64:65], v[60:61], off
	global_store_dwordx2 v[64:65], v[56:57], off offset:32
	global_store_dwordx2 v[64:65], v[48:49], off offset:256
	global_store_dwordx2 v[64:65], v[44:45], off offset:288
	global_store_dwordx2 v[74:75], v[46:47], off
	s_waitcnt vmcnt(7)
; #define PG8_GAS __attribute__((address_space(1)))
; __device__ __forceinline__ unsigned cvt_pk_bf16(float lo, float hi) { const f32x2_ v = {lo, hi}; const bf16x2_ b = __builtin_convertvector(v, bf16x2_); return __builtin_bit_cast(unsigned, b); }
;     __device__ __forceinline__ void operator()(const f32x4 (&acc)[2][2][4][2], const Unit& u, int wr, int wc, int fr, int fq) const {
;     ...
;                 u32x4 raw[2][2][2];
; #pragma unroll
;                 for (int mm = 0; mm < 2; ++mm) {
;                     const size_t off = (size_t)(u.pm * BM + ai * HALF + wr * 64 + (2 * mh + mm) * 16 + fr) * 1024 + col0;
; #pragma unroll
;                     for (int bj = 0; bj < 2; ++bj)
; #pragma unroll
;                         for (int n = 0; n < 2; ++n) {
;                             const size_t o = off + bj * HALF + n * 16;
;                             if (in_bf) { const u32x2 w = *(const PG8_GAS u32x2*)((const bf16_t*)base + o); raw[mm][bj][n].x = w.x; raw[mm][bj][n].y = w.y; }
;                             else raw[mm][bj][n] = *(const PG8_GAS u32x4*)((const float*)base + o);
;                         }
;                 }
;                 asm volatile("" ::: "memory");
; #pragma unroll
;                 for (int mm = 0; mm < 2; ++mm) {
;                     const int m = 2 * mh + mm;
;                     const size_t off = (size_t)(u.pm * BM + ai * HALF + wr * 64 + m * 16 + fr) * 1024 + col0;
; #pragma unroll
;                     for (int bj = 0; bj < 2; ++bj)
; #pragma unroll
;                         for (int n = 0; n < 2; ++n) {
;                             const size_t o = off + bj * HALF + n * 16;
;                             const u32x4 w4 = raw[mm][bj][n];
;                             f32x4 bs;
;                             if (in_bf) bs = (f32x4){bf_lo(w4.x), bf_hi(w4.x), bf_lo(w4.y), bf_hi(w4.y)};
;                             else bs = (f32x4){__uint_as_float(w4.x), __uint_as_float(w4.y), __uint_as_float(w4.z), __uint_as_float(w4.w)};
;                             const f32x4 r = bs + gv[bj][n] * acc[ai][bj][m][n];
;                             if (out_bf) { u32x2 w; w.x = cvt_pk_bf16(r[0], r[1]); w.y = cvt_pk_bf16(r[2], r[3]); *(PG8_GAS u32x2*)((bf16_t*)out + o) = w; }
;                             else *(PG8_GAS f32x4*)((float*)out + o) = r;
;                         }
;                 }
;                 asm volatile("" ::: "memory");
	v_lshlrev_b32_e32 v44, 16, v78
	v_and_b32_e32 v45, 0xffff0000, v78
	v_lshlrev_b32_e32 v46, 16, v79
	v_and_b32_e32 v47, 0xffff0000, v79
	v_pk_fma_f32 v[42:43], v[42:43], v[138:139], v[46:47]
	v_pk_fma_f32 v[40:41], v[40:41], v[136:137], v[44:45]
	s_nop 0
	v_cvt_pk_bf16_f32 v40, v40, v41
	v_cvt_pk_bf16_f32 v41, v42, v43
	global_store_dwordx2 v[74:75], v[40:41], off offset:32
	s_waitcnt vmcnt(7)
	v_lshlrev_b32_e32 v40, 16, v80
	v_and_b32_e32 v41, 0xffff0000, v80
	v_lshlrev_b32_e32 v42, 16, v81
	v_and_b32_e32 v43, 0xffff0000, v81
	v_pk_fma_f32 v[38:39], v[38:39], v[134:135], v[42:43]
	v_pk_fma_f32 v[36:37], v[36:37], v[132:133], v[40:41]
	v_add_u32_e32 v42, 0xb0, v150
	v_cvt_pk_bf16_f32 v36, v36, v37
	v_cvt_pk_bf16_f32 v37, v38, v39
	global_store_dwordx2 v[74:75], v[36:37], off offset:256
	s_waitcnt vmcnt(7)
	v_lshlrev_b32_e32 v36, 16, v82
	v_and_b32_e32 v37, 0xffff0000, v82
	v_lshlrev_b32_e32 v38, 16, v83
	v_and_b32_e32 v39, 0xffff0000, v83
	v_pk_fma_f32 v[34:35], v[34:35], v[130:131], v[38:39]
	v_pk_fma_f32 v[32:33], v[32:33], v[128:129], v[36:37]
	v_ashrrev_i32_e32 v43, 31, v42
	v_cvt_pk_bf16_f32 v32, v32, v33
	v_cvt_pk_bf16_f32 v33, v34, v35
	global_store_dwordx2 v[74:75], v[32:33], off offset:288
	v_add_u32_e32 v32, 0xa0, v150
	v_ashrrev_i32_e32 v33, 31, v32
	v_lshlrev_b64 v[32:33], 11, v[32:33]
	v_lshl_add_u64 v[32:33], s[8:9], 0, v[32:33]
	v_lshl_add_u64 v[32:33], v[32:33], 0, v[152:153]
	global_load_dwordx2 v[34:35], v[32:33], off
	global_load_dwordx2 v[36:37], v[32:33], off offset:32
	global_load_dwordx2 v[38:39], v[32:33], off offset:256
	global_load_dwordx2 v[40:41], v[32:33], off offset:288
	v_lshlrev_b64 v[42:43], 11, v[42:43]
	v_lshl_add_u64 v[42:43], s[8:9], 0, v[42:43]
	v_lshl_add_u64 v[42:43], v[42:43], 0, v[152:153]
	global_load_dwordx2 v[44:45], v[42:43], off
	global_load_dwordx2 v[46:47], v[42:43], off offset:32
	global_load_dwordx2 v[48:49], v[42:43], off offset:256
	global_load_dwordx2 v[50:51], v[42:43], off offset:288
	s_waitcnt vmcnt(7)
	v_lshlrev_b32_e32 v52, 16, v34
	v_and_b32_e32 v53, 0xffff0000, v34
	v_lshlrev_b32_e32 v34, 16, v35
	v_and_b32_e32 v35, 0xffff0000, v35
	s_waitcnt vmcnt(4)
	v_lshlrev_b32_e32 v58, 16, v40
	v_and_b32_e32 v59, 0xffff0000, v40
	v_lshlrev_b32_e32 v40, 16, v41
	v_and_b32_e32 v41, 0xffff0000, v41
	v_lshlrev_b32_e32 v54, 16, v36
	v_and_b32_e32 v55, 0xffff0000, v36
	v_lshlrev_b32_e32 v36, 16, v37
	v_and_b32_e32 v37, 0xffff0000, v37
	v_lshlrev_b32_e32 v56, 16, v38
	v_and_b32_e32 v57, 0xffff0000, v38
	v_lshlrev_b32_e32 v38, 16, v39
	v_and_b32_e32 v39, 0xffff0000, v39
	v_pk_fma_f32 v[30:31], v[30:31], v[142:143], v[34:35]
	v_pk_fma_f32 v[28:29], v[28:29], v[140:141], v[52:53]
	v_pk_fma_f32 v[14:15], v[14:15], v[130:131], v[40:41]
	v_pk_fma_f32 v[12:13], v[12:13], v[128:129], v[58:59]
	v_pk_fma_f32 v[26:27], v[26:27], v[138:139], v[36:37]
	v_pk_fma_f32 v[24:25], v[24:25], v[136:137], v[54:55]
	v_pk_fma_f32 v[22:23], v[22:23], v[134:135], v[38:39]
	v_pk_fma_f32 v[20:21], v[20:21], v[132:133], v[56:57]
	v_cvt_pk_bf16_f32 v28, v28, v29
	v_cvt_pk_bf16_f32 v29, v30, v31
	v_cvt_pk_bf16_f32 v12, v12, v13
	v_cvt_pk_bf16_f32 v13, v14, v15
	s_waitcnt vmcnt(3)
	v_lshlrev_b32_e32 v60, 16, v44
	v_cvt_pk_bf16_f32 v24, v24, v25
	v_cvt_pk_bf16_f32 v25, v26, v27
	v_cvt_pk_bf16_f32 v20, v20, v21
	v_cvt_pk_bf16_f32 v21, v22, v23
	global_store_dwordx2 v[32:33], v[28:29], off
	global_store_dwordx2 v[32:33], v[24:25], off offset:32
	global_store_dwordx2 v[32:33], v[20:21], off offset:256
	global_store_dwordx2 v[32:33], v[12:13], off offset:288
	v_and_b32_e32 v61, 0xffff0000, v44
	v_lshlrev_b32_e32 v12, 16, v45
	v_and_b32_e32 v13, 0xffff0000, v45
	v_pk_fma_f32 v[12:13], v[18:19], v[142:143], v[12:13]
	v_pk_fma_f32 v[14:15], v[16:17], v[140:141], v[60:61]
	s_nop 0
	v_cvt_pk_bf16_f32 v14, v14, v15
	v_cvt_pk_bf16_f32 v15, v12, v13
	global_store_dwordx2 v[42:43], v[14:15], off
	s_waitcnt vmcnt(7)
	v_lshlrev_b32_e32 v12, 16, v46
	v_and_b32_e32 v13, 0xffff0000, v46
	v_lshlrev_b32_e32 v14, 16, v47
	v_and_b32_e32 v15, 0xffff0000, v47
	v_pk_fma_f32 v[10:11], v[10:11], v[138:139], v[14:15]
	v_pk_fma_f32 v[8:9], v[8:9], v[136:137], v[12:13]
	s_nop 0
	v_cvt_pk_bf16_f32 v8, v8, v9
	v_cvt_pk_bf16_f32 v9, v10, v11
	global_store_dwordx2 v[42:43], v[8:9], off offset:32
	s_waitcnt vmcnt(7)
	v_lshlrev_b32_e32 v8, 16, v48
	v_and_b32_e32 v9, 0xffff0000, v48
	v_lshlrev_b32_e32 v10, 16, v49
	v_and_b32_e32 v11, 0xffff0000, v49
	v_pk_fma_f32 v[6:7], v[6:7], v[134:135], v[10:11]
	v_pk_fma_f32 v[4:5], v[4:5], v[132:133], v[8:9]
	s_nop 0
	v_cvt_pk_bf16_f32 v4, v4, v5
	v_cvt_pk_bf16_f32 v5, v6, v7
	global_store_dwordx2 v[42:43], v[4:5], off offset:256
	s_waitcnt vmcnt(7)
	v_lshlrev_b32_e32 v4, 16, v50
	v_and_b32_e32 v5, 0xffff0000, v50
	v_lshlrev_b32_e32 v6, 16, v51
	v_and_b32_e32 v7, 0xffff0000, v51
	v_pk_fma_f32 v[2:3], v[2:3], v[130:131], v[6:7]
	v_pk_fma_f32 v[0:1], v[0:1], v[128:129], v[4:5]
	s_nop 0
	v_cvt_pk_bf16_f32 v0, v0, v1
	v_cvt_pk_bf16_f32 v1, v2, v3
	global_store_dwordx2 v[42:43], v[0:1], off offset:288
	s_cbranch_vccnz .LBB0_66
	s_andn2_b64 vcc, exec, s[6:7]
	s_cbranch_vccnz .LBB0_65
	s_barrier
	s_branch .LBB0_65

; #define PG8_GAS __attribute__((address_space(1)))
;     __device__ __forceinline__ void operator()(const f32x4 (&acc)[2][2][4][2], const Unit& u, int wr, int wc, int fr, int fq) const {
;     ...
;                 float rsc[4]; u32x4 gg[4][2], qq[4][2];
; #pragma unroll
;                 for (int m = 0; m < 4; ++m) {
;                     const int row = row0 + ai * HALF + m * 16;
;                     rsc[m] = 1.f; if constexpr (MODE == 2) rsc[m] = *(const PG8_GAS float*)(rs + row);
; #pragma unroll
;                     for (int bj = 0; bj < 2; ++bj) {
;                         if constexpr (MODE == 3) {
;                             gg[m][bj] = *(const PG8_GAS u32x4*)(Gt + (size_t)row * 2048 + (add ? 1024 : 0) + col0 + bj * HALF);
;                             if (add) qq[m][bj] = *(const PG8_GAS u32x4*)(base + (size_t)row * ld + col0 + bj * HALF);
;                         }
;                     }
.LBB0_109:
	v_add_u32_e32 v250, 0x80, v210
	v_ashrrev_i32_e32 v251, 31, v250
	v_lshlrev_b64 v[250:251], 12, v[250:251]
	v_lshl_add_u64 v[250:251], v[212:213], 0, v[250:251]
	global_load_dword v252, v[250:251], off
	global_load_dword v252, v[250:251], off offset:256
	s_mov_b64 s[98:99], 0x10000
	v_lshl_add_u64 v[250:251], v[250:251], 0, s[98:99]
	global_load_dword v252, v[250:251], off
	global_load_dword v252, v[250:251], off offset:256
	s_mov_b64 s[98:99], 0x10000
	v_lshl_add_u64 v[250:251], v[250:251], 0, s[98:99]
	global_load_dword v252, v[250:251], off
	global_load_dword v252, v[250:251], off offset:256
	s_mov_b64 s[98:99], 0x10000
	v_lshl_add_u64 v[250:251], v[250:251], 0, s[98:99]
	global_load_dword v252, v[250:251], off
	global_load_dword v252, v[250:251], off offset:256
	s_and_b64 s[100:101], s[44:45], exec
	s_cbranch_scc0 .Lpf_skip_br
	s_mov_b64 s[98:99], 0x40000
	v_lshl_add_u64 v[250:251], v[222:223], 0, s[98:99]
	global_load_dword v252, v[250:251], off
	global_load_dword v252, v[250:251], off offset:256
	s_mov_b64 s[98:99], 0x40000
	v_lshl_add_u64 v[250:251], v[220:221], 0, s[98:99]
	global_load_dword v252, v[250:251], off
	global_load_dword v252, v[250:251], off offset:256
	s_mov_b64 s[98:99], 0x40000
	v_lshl_add_u64 v[250:251], v[218:219], 0, s[98:99]
	global_load_dword v252, v[250:251], off
	global_load_dword v252, v[250:251], off offset:256
	s_mov_b64 s[98:99], 0x40000
	v_lshl_add_u64 v[250:251], v[216:217], 0, s[98:99]
	global_load_dword v252, v[250:251], off
	global_load_dword v252, v[250:251], off offset:256

; #define PG8_GAS __attribute__((address_space(1)))
;     __device__ __forceinline__ void operator()(const f32x4 (&acc)[2][2][4][2], const Unit& u, int wr, int wc, int fr, int fq) const {
;     ...
; #pragma unroll
;                 for (int mm = 0; mm < 2; ++mm) {
;                     const size_t off = (size_t)(u.pm * BM + ai * HALF + wr * 64 + (2 * mh + mm) * 16 + fr) * 1024 + col0;
; #pragma unroll
;                     for (int bj = 0; bj < 2; ++bj)
; #pragma unroll
;                         for (int n = 0; n < 2; ++n) {
;                             const size_t o = off + bj * HALF + n * 16;
;                             if (in_bf) { const u32x2 w = *(const PG8_GAS u32x2*)((const bf16_t*)base + o); raw[mm][bj][n].x = w.x; raw[mm][bj][n].y = w.y; }
;                             else raw[mm][bj][n] = *(const PG8_GAS u32x4*)((const float*)base + o);
;                         }
;                 }
.LBB0_382:
	s_and_b64 s[100:101], s[12:13], exec
	s_cbranch_scc0 .Lpf_skip_ffnb
	s_mov_b64 s[98:99], 0x8000
	v_lshl_add_u64 v[250:251], v[184:185], 0, s[98:99]
	global_load_dword v252, v[250:251], off
	global_load_dword v252, v[250:251], off offset:256
	s_mov_b64 s[98:99], 0x8000
	v_lshl_add_u64 v[250:251], v[250:251], 0, s[98:99]
	global_load_dword v252, v[250:251], off
	global_load_dword v252, v[250:251], off offset:256
	s_mov_b64 s[98:99], 0x28000
	v_lshl_add_u64 v[250:251], v[250:251], 0, s[98:99]
	global_load_dword v252, v[250:251], off
	global_load_dword v252, v[250:251], off offset:256
	s_mov_b64 s[98:99], 0x8000
	v_lshl_add_u64 v[250:251], v[250:251], 0, s[98:99]
	global_load_dword v252, v[250:251], off
	global_load_dword v252, v[250:251], off offset:256
	s_mov_b64 s[98:99], 0x8000
	v_lshl_add_u64 v[250:251], v[250:251], 0, s[98:99]
	global_load_dword v252, v[250:251], off
	global_load_dword v252, v[250:251], off offset:256
	s_mov_b64 s[98:99], 0x8000
	v_lshl_add_u64 v[250:251], v[250:251], 0, s[98:99]
	global_load_dword v252, v[250:251], off
	global_load_dword v252, v[250:251], off offset:256

; __global__ void __launch_bounds__(NTHR, 2) fwd_megakernel(Args args) {
	.amdhsa_kernel _Z14fwd_megakernel4Args
		.amdhsa_group_segment_fixed_size 0
		.amdhsa_private_segment_fixed_size 0
		.amdhsa_kernarg_size 464
		.amdhsa_user_sgpr_count 2
		.amdhsa_user_sgpr_dispatch_ptr 0
		.amdhsa_user_sgpr_queue_ptr 0
		.amdhsa_user_sgpr_kernarg_segment_ptr 1
		.amdhsa_user_sgpr_dispatch_id 0
		.amdhsa_user_sgpr_kernarg_preload_length 0
		.amdhsa_user_sgpr_kernarg_preload_offset 0
		.amdhsa_user_sgpr_private_segment_size 0
		.amdhsa_uses_dynamic_stack 0
		.amdhsa_enable_private_segment 0
		.amdhsa_system_sgpr_workgroup_id_x 1
		.amdhsa_system_sgpr_workgroup_id_y 0
		.amdhsa_system_sgpr_workgroup_id_z 0
		.amdhsa_system_sgpr_workgroup_info 0
		.amdhsa_system_vgpr_workitem_id 2
		.amdhsa_next_free_vgpr 256
		.amdhsa_next_free_sgpr 102
		.amdhsa_accum_offset 256
		.amdhsa_reserve_vcc 1
		.amdhsa_float_round_mode_32 0
		.amdhsa_float_round_mode_16_64 0
		.amdhsa_float_denorm_mode_32 3
		.amdhsa_float_denorm_mode_16_64 3
		.amdhsa_dx10_clamp 1
		.amdhsa_ieee_mode 1
		.amdhsa_fp16_overflow 0
		.amdhsa_tg_split 0
		.amdhsa_exception_fp_ieee_invalid_op 0
		.amdhsa_exception_fp_denorm_src 0
		.amdhsa_exception_fp_ieee_div_zero 0
		.amdhsa_exception_fp_ieee_overflow 0
		.amdhsa_exception_fp_ieee_underflow 0
		.amdhsa_exception_fp_ieee_inexact 0
		.amdhsa_exception_int_div_zero 0
	.end_amdhsa_kernel

; __global__ void __launch_bounds__(NTHR, 2) fwd_megakernel(Args args) {
amdhsa.kernels:
  - .agpr_count:     0
    .args:
      - .offset:         0
        .size:           208
        .value_kind:     by_value
      - .offset:         208
        .size:           4
        .value_kind:     hidden_block_count_x
      - .offset:         212
        .size:           4
        .value_kind:     hidden_block_count_y
      - .offset:         216
        .size:           4
        .value_kind:     hidden_block_count_z
      - .offset:         220
        .size:           2
        .value_kind:     hidden_group_size_x
      - .offset:         222
        .size:           2
        .value_kind:     hidden_group_size_y
      - .offset:         224
        .size:           2
        .value_kind:     hidden_group_size_z
      - .offset:         226
        .size:           2
        .value_kind:     hidden_remainder_x
      - .offset:         228
        .size:           2
        .value_kind:     hidden_remainder_y
      - .offset:         230
        .size:           2
        .value_kind:     hidden_remainder_z
      - .offset:         248
        .size:           8
        .value_kind:     hidden_global_offset_x
      - .offset:         256
        .size:           8
        .value_kind:     hidden_global_offset_y
      - .offset:         264
        .size:           8
        .value_kind:     hidden_global_offset_z
      - .offset:         272
        .size:           2
        .value_kind:     hidden_grid_dims
      - .offset:         296
        .size:           8
        .value_kind:     hidden_multigrid_sync_arg
      - .offset:         328
        .size:           4
        .value_kind:     hidden_dynamic_lds_size
    .group_segment_fixed_size: 0
    .kernarg_segment_align: 8
    .kernarg_segment_size: 464
    .language:       OpenCL C
    .language_version:
      - 2
      - 0
    .max_flat_workgroup_size: 512
    .name:           _Z14fwd_megakernel4Args
    .private_segment_fixed_size: 0
    .sgpr_count:     108
    .sgpr_spill_count: 49
    .symbol:         _Z14fwd_megakernel4Args.kd
    .uniform_work_group_size: 1
    .uses_dynamic_stack: false
    .vgpr_count:     256
    .vgpr_spill_count: 0
    .wavefront_size: 64
